# FoX forget-bias LDS reads issued with the K fragment reads, on top of the permlane row max
# baseline (speedup 1.0000x reference)
; DEVI unsigned pk_bf16(float lo, float hi) { unsigned r; asm("v_cvt_pk_bf16_f32 %0, %1, %2" : "=v"(r) : "v"(lo), "v"(hi)); return r; }
; DEVI bf16x8 mk8(uint2 a, uint2 b) { union { uint4 u; bf16x8 v; } c; c.u = make_uint4(a.x, a.y, b.x, b.y); return c.v; }
; template <int DK, bool BIAS> ...
;     ...
;       for (int qi = 0; qi < 2; ++qi) {
;         float mx = -3e38f;
;         if (BIAS) {
; #pragma unroll
;           for (int kt = 0; kt < 4; ++kt) { const f32x4 nf = *(const f32x4*)(fkm + buf * 64 + 16 * kt + 4 * fq);
; #pragma unroll
;             for (int r = 0; r < 4; ++r) { const float t = fmaf(S[kt][qi][r], sc2, nf[r]); S[kt][qi][r] = t; mx = fmaxf(mx, t); } }
;         } else {
; #pragma unroll
;           for (int kt = 0; kt < 4; ++kt)
; #pragma unroll
;             for (int r = 0; r < 4; ++r) mx = fmaxf(mx, S[kt][qi][r]);
;           mx *= sc2;
;         }
;         mx = fmaxf(mx, __shfl_xor(mx, 16)); mx = fmaxf(mx, __shfl_xor(mx, 32));
;         const float mold = mrun[qi], mnew = fmaxf(mold, mx);
;         mrun[qi] = mnew;
;         float ps = 0.f;
; #pragma unroll
;         for (int kt = 0; kt < 4; ++kt)
; #pragma unroll
;           for (int r = 0; r < 4; ++r) { const float pv = BIAS ? __builtin_amdgcn_exp2f(S[kt][qi][r] - mnew) : __builtin_amdgcn_exp2f(fmaf(S[kt][qi][r], sc2, -mnew)); S[kt][qi][r] = pv; ps += pv; }
;         {
;           const float alpha = __builtin_amdgcn_exp2f(mold - mnew);
;           lrun[qi] *= alpha;
; #pragma unroll
;           for (int et = 0; et < 4; ++et) O[et][qi] *= alpha;
;         }
;         lrun[qi] += ps;
; #pragma unroll
;         for (int k2 = 0; k2 < 2; ++k2) { uint2 lo, hi; lo.x = pk_bf16(S[2 * k2][qi][0], S[2 * k2][qi][1]); lo.y = pk_bf16(S[2 * k2][qi][2], S[2 * k2][qi][3]);
;           hi.x = pk_bf16(S[2 * k2 + 1][qi][0], S[2 * k2 + 1][qi][1]); hi.y = pk_bf16(S[2 * k2 + 1][qi][2], S[2 * k2 + 1][qi][3]); pf[qi][k2] = mk8(lo, hi); }
;       }
; #pragma unroll
;       for (int k2 = 0; k2 < 2; ++k2)
; #pragma unroll
;         for (int et = 0; et < 4; ++et) {
;           const uint2 v0 = *(const uint2*)(Vtm + (buf * 64 + 16 * et + fr) * 72 + 32 * k2 + 4 * fq), v1 = *(const uint2*)(Vtm + (buf * 64 + 16 * et + fr) * 72 + 32 * k2 + 16 + 4 * fq);
;           const bf16x8 va = mk8(v0, v1);
.LBB0_1776:
	s_or_b64 exec, exec, s[18:19]
	s_mov_b32 s100, 0x3e38aa3b
	s_mov_b32 s101, 0x3e38aa3b
	v_lshlrev_b32_e32 v250, 2, v186
	s_waitcnt lgkmcnt(3)
	v_pk_fma_f32 v[210:211], v[80:81], s[100:101], v[174:175]
	v_pk_fma_f32 v[212:213], v[82:83], s[100:101], v[176:177]
	v_pk_fma_f32 v[226:227], v[64:65], s[100:101], v[174:175]
	v_pk_fma_f32 v[228:229], v[66:67], s[100:101], v[176:177]
	s_waitcnt lgkmcnt(2)
	v_pk_fma_f32 v[214:215], v[86:87], s[100:101], v[194:195]
	v_pk_fma_f32 v[216:217], v[88:89], s[100:101], v[196:197]
	v_pk_fma_f32 v[230:231], v[68:69], s[100:101], v[194:195]
	v_pk_fma_f32 v[232:233], v[70:71], s[100:101], v[196:197]
	s_waitcnt lgkmcnt(1)
	v_pk_fma_f32 v[218:219], v[90:91], s[100:101], v[242:243]
	v_pk_fma_f32 v[220:221], v[92:93], s[100:101], v[244:245]
	v_pk_fma_f32 v[234:235], v[72:73], s[100:101], v[242:243]
	v_pk_fma_f32 v[236:237], v[74:75], s[100:101], v[244:245]
	s_waitcnt lgkmcnt(0)
	v_pk_fma_f32 v[222:223], v[94:95], s[100:101], v[246:247]
	v_pk_fma_f32 v[224:225], v[96:97], s[100:101], v[248:249]
	v_pk_fma_f32 v[238:239], v[76:77], s[100:101], v[246:247]
	v_pk_fma_f32 v[240:241], v[78:79], s[100:101], v[248:249]
	v_max3_f32 v84, v210, s31, v211
	v_max3_f32 v85, v226, s31, v227
	v_max3_f32 v84, v84, v212, v213
	v_max3_f32 v85, v85, v228, v229
	v_max3_f32 v84, v84, v214, v215
	v_max3_f32 v85, v85, v230, v231
	v_max3_f32 v84, v84, v216, v217
	v_max3_f32 v85, v85, v232, v233
	v_max3_f32 v84, v84, v218, v219
	v_max3_f32 v85, v85, v234, v235
	v_max3_f32 v84, v84, v220, v221
	v_max3_f32 v85, v85, v236, v237
	v_max3_f32 v84, v84, v222, v223
	v_max3_f32 v85, v85, v238, v239
	v_max3_f32 v84, v84, v224, v225
	v_max3_f32 v85, v85, v240, v241
	v_mov_b32_e32 v86, v84
	v_mov_b32_e32 v87, v85
	s_nop 1
	v_permlane16_swap_b32_e32 v86, v84
	v_permlane16_swap_b32_e32 v87, v85
	v_max_f32_e32 v84, v84, v86
	v_max_f32_e32 v85, v85, v87
	v_mov_b32_e32 v86, v84
	v_mov_b32_e32 v87, v85
	s_nop 1
	v_permlane32_swap_b32_e32 v86, v84
	v_permlane32_swap_b32_e32 v87, v85
	v_max3_f32 v131, v114, v84, v86
	v_max3_f32 v173, v112, v85, v87
	v_sub_f32_e32 v84, v114, v131
	v_sub_f32_e32 v85, v112, v173
	v_exp_f32_e32 v126, v84
	v_exp_f32_e32 v82, v85
	v_sub_f32_e32 v86, 0, v131
	v_sub_f32_e32 v80, 0, v173
	v_pk_add_f32 v[210:211], v[210:211], v[86:87] op_sel_hi:[1,0]
	v_pk_add_f32 v[212:213], v[212:213], v[86:87] op_sel_hi:[1,0]
	v_pk_add_f32 v[226:227], v[226:227], v[80:81] op_sel_hi:[1,0]
	v_pk_add_f32 v[228:229], v[228:229], v[80:81] op_sel_hi:[1,0]
	v_pk_add_f32 v[214:215], v[214:215], v[86:87] op_sel_hi:[1,0]
	v_pk_add_f32 v[216:217], v[216:217], v[86:87] op_sel_hi:[1,0]
	v_pk_add_f32 v[230:231], v[230:231], v[80:81] op_sel_hi:[1,0]
	v_pk_add_f32 v[232:233], v[232:233], v[80:81] op_sel_hi:[1,0]
	v_pk_add_f32 v[218:219], v[218:219], v[86:87] op_sel_hi:[1,0]
	v_pk_add_f32 v[220:221], v[220:221], v[86:87] op_sel_hi:[1,0]
	v_pk_add_f32 v[234:235], v[234:235], v[80:81] op_sel_hi:[1,0]
	v_pk_add_f32 v[236:237], v[236:237], v[80:81] op_sel_hi:[1,0]
	v_pk_add_f32 v[222:223], v[222:223], v[86:87] op_sel_hi:[1,0]
	v_pk_add_f32 v[224:225], v[224:225], v[86:87] op_sel_hi:[1,0]
	v_pk_add_f32 v[238:239], v[238:239], v[80:81] op_sel_hi:[1,0]
	v_pk_add_f32 v[240:241], v[240:241], v[80:81] op_sel_hi:[1,0]
	v_exp_f32_e32 v155, v210
	v_exp_f32_e32 v154, v226
	v_exp_f32_e32 v157, v211
	v_exp_f32_e32 v156, v227
	v_exp_f32_e32 v151, v212
	v_exp_f32_e32 v150, v228
	v_exp_f32_e32 v153, v213
	v_exp_f32_e32 v152, v229
	v_exp_f32_e32 v117, v214
	v_exp_f32_e32 v116, v230
	v_exp_f32_e32 v119, v215
	v_exp_f32_e32 v118, v231
	v_exp_f32_e32 v123, v216
	v_exp_f32_e32 v122, v232
	v_exp_f32_e32 v121, v217
	v_exp_f32_e32 v120, v233
	v_exp_f32_e32 v125, v218
	v_exp_f32_e32 v124, v234
	v_exp_f32_e32 v89, v219
	v_exp_f32_e32 v88, v235
	v_exp_f32_e32 v95, v220
	v_exp_f32_e32 v94, v236
	v_exp_f32_e32 v115, v221
	v_exp_f32_e32 v114, v237
	v_exp_f32_e32 v93, v222
	v_exp_f32_e32 v92, v238
	v_exp_f32_e32 v113, v223
	v_exp_f32_e32 v112, v239
	v_exp_f32_e32 v91, v224
	v_exp_f32_e32 v90, v240
	v_exp_f32_e32 v97, v225
	v_exp_f32_e32 v96, v241
	v_add_u32_e32 v242, 0x4800, v170
	v_add_u32_e32 v243, 0x5000, v170
	v_add_u32_e32 v244, 0x5800, v170
	v_add_u32_e32 v245, 0x6000, v170
	ds_read2_b64 v[210:213], v242 offset1:4
	ds_read2_b64 v[214:217], v243 offset0:32 offset1:36
	ds_read2_b64 v[218:221], v244 offset0:64 offset1:68
	ds_read2_b64 v[222:225], v245 offset0:96 offset1:100
	ds_read2_b64 v[226:229], v242 offset0:8 offset1:12
	ds_read2_b64 v[230:233], v243 offset0:40 offset1:44
	ds_read2_b64 v[234:237], v244 offset0:72 offset1:76
	ds_read2_b64 v[238:241], v245 offset0:104 offset1:108
	v_pk_mul_f32 v[202:203], v[52:53], v[126:127] op_sel_hi:[1,0]
	v_pk_mul_f32 v[52:53], v[56:57], v[126:127] op_sel_hi:[1,0]
	v_pk_mul_f32 v[198:199], v[48:49], v[126:127] op_sel_hi:[1,0]
	v_pk_mul_f32 v[48:49], v[60:61], v[126:127] op_sel_hi:[1,0]
	v_pk_mul_f32 v[200:201], v[50:51], v[126:127] op_sel_hi:[1,0]
	v_pk_mul_f32 v[204:205], v[54:55], v[126:127] op_sel_hi:[1,0]
	v_pk_add_f32 v[64:65], v[154:155], 0 op_sel_hi:[1,0]
	v_pk_add_f32 v[80:81], v[156:157], v[64:65]
	v_pk_mul_f32 v[46:47], v[46:47], v[82:83] op_sel_hi:[1,0]
	v_pk_mul_f32 v[44:45], v[44:45], v[82:83] op_sel_hi:[1,0]
	v_pk_mul_f32 v[54:55], v[58:59], v[126:127] op_sel_hi:[1,0]
	v_cvt_pk_bf16_f32 v56, v155, v157
	v_cvt_pk_bf16_f32 v57, v151, v153
	v_cvt_pk_bf16_f32 v58, v117, v119
	v_cvt_pk_bf16_f32 v59, v123, v121
	v_cvt_pk_bf16_f32 v68, v154, v156
	s_waitcnt lgkmcnt(7)
; DEVI unsigned pk_bf16(float lo, float hi) { unsigned r; asm("v_cvt_pk_bf16_f32 %0, %1, %2" : "=v"(r) : "v"(lo), "v"(hi)); return r; }
; DEVI bf16x8 mk8(uint2 a, uint2 b) { union { uint4 u; bf16x8 v; } c; c.u = make_uint4(a.x, a.y, b.x, b.y); return c.v; }
; #define MFMA(a, b, c) __builtin_amdgcn_mfma_f32_16x16x32_bf16((a), (b), (c), 0, 0, 0)
; template <int DK, bool BIAS> ...
;     ...
;         {
;           const float alpha = __builtin_amdgcn_exp2f(mold - mnew);
;           lrun[qi] *= alpha;
; #pragma unroll
;           for (int et = 0; et < 4; ++et) O[et][qi] *= alpha;
;         }
;         lrun[qi] += ps;
; #pragma unroll
;         for (int k2 = 0; k2 < 2; ++k2) { uint2 lo, hi; lo.x = pk_bf16(S[2 * k2][qi][0], S[2 * k2][qi][1]); lo.y = pk_bf16(S[2 * k2][qi][2], S[2 * k2][qi][3]);
;           hi.x = pk_bf16(S[2 * k2 + 1][qi][0], S[2 * k2 + 1][qi][1]); hi.y = pk_bf16(S[2 * k2 + 1][qi][2], S[2 * k2 + 1][qi][3]); pf[qi][k2] = mk8(lo, hi); }
;       }
; #pragma unroll
;       for (int k2 = 0; k2 < 2; ++k2)
; #pragma unroll
;         for (int et = 0; et < 4; ++et) {
;           const uint2 v0 = *(const uint2*)(Vtm + (buf * 64 + 16 * et + fr) * 72 + 32 * k2 + 4 * fq), v1 = *(const uint2*)(Vtm + (buf * 64 + 16 * et + fr) * 72 + 32 * k2 + 16 + 4 * fq);
;           const bf16x8 va = mk8(v0, v1);
; #pragma unroll
;           for (int qi = 0; qi < 2; ++qi) O[et][qi] = MFMA(va, pf[qi][k2], O[et][qi]);
;         }
	v_mfma_f32_16x16x32_bf16 v[76:79], v[210:213], v[56:59], v[198:201]
	v_cvt_pk_bf16_f32 v69, v150, v152
	v_cvt_pk_bf16_f32 v70, v116, v118
	v_cvt_pk_bf16_f32 v71, v122, v120
	v_pk_mul_f32 v[42:43], v[42:43], v[82:83] op_sel_hi:[1,0]
	s_nop 0
	v_mfma_f32_16x16x32_bf16 v[44:47], v[210:213], v[68:71], v[44:47]
	v_pk_mul_f32 v[40:41], v[40:41], v[82:83] op_sel_hi:[1,0]
	s_waitcnt lgkmcnt(6)
	v_mfma_f32_16x16x32_bf16 v[84:87], v[214:217], v[56:59], v[202:205]
	v_pk_mul_f32 v[50:51], v[62:63], v[126:127] op_sel_hi:[1,0]
	v_mfma_f32_16x16x32_bf16 v[40:43], v[214:217], v[68:71], v[40:43]
	v_pk_mul_f32 v[38:39], v[38:39], v[82:83] op_sel_hi:[1,0]
	v_pk_mul_f32 v[36:37], v[36:37], v[82:83] op_sel_hi:[1,0]
	s_waitcnt lgkmcnt(5)
	v_mfma_f32_16x16x32_bf16 v[154:157], v[218:221], v[56:59], v[52:55]
	v_pk_mul_f32 v[34:35], v[34:35], v[82:83] op_sel_hi:[1,0]
	v_pk_mul_f32 v[32:33], v[32:33], v[82:83] op_sel_hi:[1,0]
	v_cvt_pk_bf16_f32 v60, v125, v89
	v_mfma_f32_16x16x32_bf16 v[36:39], v[218:221], v[68:71], v[36:39]
	s_waitcnt lgkmcnt(4)
	v_mfma_f32_16x16x32_bf16 v[64:67], v[222:225], v[56:59], v[48:51]
	v_cvt_pk_bf16_f32 v61, v95, v115
	v_cvt_pk_bf16_f32 v62, v93, v113
	v_cvt_pk_bf16_f32 v63, v91, v97
	s_nop 0
	v_mfma_f32_16x16x32_bf16 v[32:35], v[222:225], v[68:71], v[32:35]
	v_cvt_pk_bf16_f32 v68, v124, v88
	v_cvt_pk_bf16_f32 v69, v94, v114
	s_waitcnt lgkmcnt(3)
	v_mfma_f32_16x16x32_bf16 v[48:51], v[226:229], v[60:63], v[76:79]
	v_cvt_pk_bf16_f32 v70, v92, v112
	v_cvt_pk_bf16_f32 v71, v90, v96
	s_nop 1
	v_mfma_f32_16x16x32_bf16 v[44:47], v[226:229], v[68:71], v[44:47]
	v_pk_add_f32 v[52:53], v[150:151], v[80:81]
	v_mov_b32_e32 v83, v126
	v_pk_add_f32 v[76:77], v[152:153], v[52:53]
	s_waitcnt lgkmcnt(2)
	v_mfma_f32_16x16x32_bf16 v[52:55], v[230:233], v[60:63], v[84:87]
	v_pk_add_f32 v[76:77], v[116:117], v[76:77]
	v_pk_add_f32 v[76:77], v[118:119], v[76:77]
	v_mfma_f32_16x16x32_bf16 v[40:43], v[230:233], v[68:71], v[40:43]
	v_pk_add_f32 v[76:77], v[122:123], v[76:77]
	v_pk_add_f32 v[56:57], v[120:121], v[76:77]
	v_pk_add_f32 v[80:81], v[124:125], v[56:57]
	s_waitcnt lgkmcnt(1)
	v_mfma_f32_16x16x32_bf16 v[56:59], v[234:237], v[60:63], v[154:157]
	v_pk_add_f32 v[80:81], v[88:89], v[80:81]
	v_pk_add_f32 v[80:81], v[94:95], v[80:81]
	v_mfma_f32_16x16x32_bf16 v[36:39], v[234:237], v[68:71], v[36:39]
	v_pk_add_f32 v[80:81], v[114:115], v[80:81]
	v_mov_b32_e32 v114, v131
	v_pk_add_f32 v[72:73], v[92:93], v[80:81]
	s_waitcnt lgkmcnt(0)
	v_mfma_f32_16x16x32_bf16 v[60:63], v[238:241], v[60:63], v[64:67]
	v_pk_add_f32 v[72:73], v[112:113], v[72:73]
	v_mov_b32_e32 v112, v173
	v_mfma_f32_16x16x32_bf16 v[32:35], v[238:241], v[68:71], v[32:35]
	v_pk_add_f32 v[64:65], v[90:91], v[72:73]
	v_pk_add_f32 v[64:65], v[96:97], v[64:65]
	s_nop 0
	v_pk_fma_f32 v[106:107], v[106:107], v[82:83], v[64:65]

; DEVI unsigned pk_bf16(float lo, float hi) { unsigned r; asm("v_cvt_pk_bf16_f32 %0, %1, %2" : "=v"(r) : "v"(lo), "v"(hi)); return r; }
; DEVI bf16x8 mk8(uint2 a, uint2 b) { union { uint4 u; bf16x8 v; } c; c.u = make_uint4(a.x, a.y, b.x, b.y); return c.v; }
; template <int DK, bool BIAS> ...
;     ...
;       for (int qi = 0; qi < 2; ++qi) {
;         float mx = -3e38f;
;         if (BIAS) {
; #pragma unroll
;           for (int kt = 0; kt < 4; ++kt) { const f32x4 nf = *(const f32x4*)(fkm + buf * 64 + 16 * kt + 4 * fq);
; #pragma unroll
;             for (int r = 0; r < 4; ++r) { const float t = fmaf(S[kt][qi][r], sc2, nf[r]); S[kt][qi][r] = t; mx = fmaxf(mx, t); } }
;         } else {
; #pragma unroll
;           for (int kt = 0; kt < 4; ++kt)
; #pragma unroll
;             for (int r = 0; r < 4; ++r) mx = fmaxf(mx, S[kt][qi][r]);
;           mx *= sc2;
;         }
;         mx = fmaxf(mx, __shfl_xor(mx, 16)); mx = fmaxf(mx, __shfl_xor(mx, 32));
;         const float mold = mrun[qi], mnew = fmaxf(mold, mx);
;         mrun[qi] = mnew;
;         float ps = 0.f;
; #pragma unroll
;         for (int kt = 0; kt < 4; ++kt)
; #pragma unroll
;           for (int r = 0; r < 4; ++r) { const float pv = BIAS ? __builtin_amdgcn_exp2f(S[kt][qi][r] - mnew) : __builtin_amdgcn_exp2f(fmaf(S[kt][qi][r], sc2, -mnew)); S[kt][qi][r] = pv; ps += pv; }
;         {
;           const float alpha = __builtin_amdgcn_exp2f(mold - mnew);
;           lrun[qi] *= alpha;
; #pragma unroll
;           for (int et = 0; et < 4; ++et) O[et][qi] *= alpha;
;         }
;         lrun[qi] += ps;
; #pragma unroll
;         for (int k2 = 0; k2 < 2; ++k2) { uint2 lo, hi; lo.x = pk_bf16(S[2 * k2][qi][0], S[2 * k2][qi][1]); lo.y = pk_bf16(S[2 * k2][qi][2], S[2 * k2][qi][3]);
;           hi.x = pk_bf16(S[2 * k2 + 1][qi][0], S[2 * k2 + 1][qi][1]); hi.y = pk_bf16(S[2 * k2 + 1][qi][2], S[2 * k2 + 1][qi][3]); pf[qi][k2] = mk8(lo, hi); }
;       }
; #pragma unroll
;       for (int k2 = 0; k2 < 2; ++k2)
; #pragma unroll
;         for (int et = 0; et < 4; ++et) {
;           const uint2 v0 = *(const uint2*)(Vtm + (buf * 64 + 16 * et + fr) * 72 + 32 * k2 + 4 * fq), v1 = *(const uint2*)(Vtm + (buf * 64 + 16 * et + fr) * 72 + 32 * k2 + 16 + 4 * fq);
;           const bf16x8 va = mk8(v0, v1);
.LBB0_1797:
	s_or_b64 exec, exec, s[18:19]
	s_mov_b32 s100, 0x3e38aa3b
	s_mov_b32 s101, 0x3e38aa3b
	v_lshlrev_b32_e32 v250, 2, v186
	s_waitcnt lgkmcnt(3)
	v_pk_fma_f32 v[210:211], v[80:81], s[100:101], v[174:175]
	v_pk_fma_f32 v[212:213], v[82:83], s[100:101], v[176:177]
	v_pk_fma_f32 v[226:227], v[64:65], s[100:101], v[174:175]
	v_pk_fma_f32 v[228:229], v[66:67], s[100:101], v[176:177]
	s_waitcnt lgkmcnt(2)
	v_pk_fma_f32 v[214:215], v[86:87], s[100:101], v[194:195]
	v_pk_fma_f32 v[216:217], v[88:89], s[100:101], v[196:197]
	v_pk_fma_f32 v[230:231], v[68:69], s[100:101], v[194:195]
	v_pk_fma_f32 v[232:233], v[70:71], s[100:101], v[196:197]
	s_waitcnt lgkmcnt(1)
	v_pk_fma_f32 v[218:219], v[90:91], s[100:101], v[242:243]
	v_pk_fma_f32 v[220:221], v[92:93], s[100:101], v[244:245]
	v_pk_fma_f32 v[234:235], v[72:73], s[100:101], v[242:243]
	v_pk_fma_f32 v[236:237], v[74:75], s[100:101], v[244:245]
	s_waitcnt lgkmcnt(0)
	v_pk_fma_f32 v[222:223], v[94:95], s[100:101], v[246:247]
	v_pk_fma_f32 v[224:225], v[96:97], s[100:101], v[248:249]
	v_pk_fma_f32 v[238:239], v[76:77], s[100:101], v[246:247]
	v_pk_fma_f32 v[240:241], v[78:79], s[100:101], v[248:249]
	v_max3_f32 v84, v210, s31, v211
	v_max3_f32 v85, v226, s31, v227
	v_max3_f32 v84, v84, v212, v213
	v_max3_f32 v85, v85, v228, v229
	v_max3_f32 v84, v84, v214, v215
	v_max3_f32 v85, v85, v230, v231
	v_max3_f32 v84, v84, v216, v217
	v_max3_f32 v85, v85, v232, v233
	v_max3_f32 v84, v84, v218, v219
	v_max3_f32 v85, v85, v234, v235
	v_max3_f32 v84, v84, v220, v221
	v_max3_f32 v85, v85, v236, v237
	v_max3_f32 v84, v84, v222, v223
	v_max3_f32 v85, v85, v238, v239
	v_max3_f32 v84, v84, v224, v225
	v_max3_f32 v85, v85, v240, v241
	v_mov_b32_e32 v86, v84
	v_mov_b32_e32 v87, v85
	s_nop 1
	v_permlane16_swap_b32_e32 v86, v84
	v_permlane16_swap_b32_e32 v87, v85
	v_max_f32_e32 v84, v84, v86
	v_max_f32_e32 v85, v85, v87
	v_mov_b32_e32 v86, v84
	v_mov_b32_e32 v87, v85
	s_nop 1
	v_permlane32_swap_b32_e32 v86, v84
	v_permlane32_swap_b32_e32 v87, v85
	v_max3_f32 v131, v114, v84, v86
	v_max3_f32 v173, v112, v85, v87
	v_sub_f32_e32 v84, v114, v131
	v_sub_f32_e32 v85, v112, v173
	v_exp_f32_e32 v126, v84
	v_exp_f32_e32 v82, v85
	v_sub_f32_e32 v86, 0, v131
	v_sub_f32_e32 v80, 0, v173
	v_pk_add_f32 v[210:211], v[210:211], v[86:87] op_sel_hi:[1,0]
	v_pk_add_f32 v[212:213], v[212:213], v[86:87] op_sel_hi:[1,0]
	v_pk_add_f32 v[226:227], v[226:227], v[80:81] op_sel_hi:[1,0]
	v_pk_add_f32 v[228:229], v[228:229], v[80:81] op_sel_hi:[1,0]
	v_pk_add_f32 v[214:215], v[214:215], v[86:87] op_sel_hi:[1,0]
	v_pk_add_f32 v[216:217], v[216:217], v[86:87] op_sel_hi:[1,0]
	v_pk_add_f32 v[230:231], v[230:231], v[80:81] op_sel_hi:[1,0]
	v_pk_add_f32 v[232:233], v[232:233], v[80:81] op_sel_hi:[1,0]
	v_pk_add_f32 v[218:219], v[218:219], v[86:87] op_sel_hi:[1,0]
	v_pk_add_f32 v[220:221], v[220:221], v[86:87] op_sel_hi:[1,0]
	v_pk_add_f32 v[234:235], v[234:235], v[80:81] op_sel_hi:[1,0]
	v_pk_add_f32 v[236:237], v[236:237], v[80:81] op_sel_hi:[1,0]
	v_pk_add_f32 v[222:223], v[222:223], v[86:87] op_sel_hi:[1,0]
	v_pk_add_f32 v[224:225], v[224:225], v[86:87] op_sel_hi:[1,0]
	v_pk_add_f32 v[238:239], v[238:239], v[80:81] op_sel_hi:[1,0]
	v_pk_add_f32 v[240:241], v[240:241], v[80:81] op_sel_hi:[1,0]
	v_exp_f32_e32 v155, v210
	v_exp_f32_e32 v154, v226
	v_exp_f32_e32 v157, v211
	v_exp_f32_e32 v156, v227
	v_exp_f32_e32 v151, v212
	v_exp_f32_e32 v150, v228
	v_exp_f32_e32 v153, v213
	v_exp_f32_e32 v152, v229
	v_exp_f32_e32 v117, v214
	v_exp_f32_e32 v116, v230
	v_exp_f32_e32 v119, v215
	v_exp_f32_e32 v118, v231
	v_exp_f32_e32 v123, v216
	v_exp_f32_e32 v122, v232
	v_exp_f32_e32 v121, v217
	v_exp_f32_e32 v120, v233
	v_exp_f32_e32 v125, v218
	v_exp_f32_e32 v124, v234
	v_exp_f32_e32 v89, v219
	v_exp_f32_e32 v88, v235
	v_exp_f32_e32 v95, v220
	v_exp_f32_e32 v94, v236
	v_exp_f32_e32 v115, v221
	v_exp_f32_e32 v114, v237
	v_exp_f32_e32 v93, v222
	v_exp_f32_e32 v92, v238
	v_exp_f32_e32 v113, v223
	v_exp_f32_e32 v112, v239
	v_exp_f32_e32 v91, v224
	v_exp_f32_e32 v90, v240
	v_exp_f32_e32 v97, v225
	v_exp_f32_e32 v96, v241
	v_add_u32_e32 v242, 0x6800, v170
	v_add_u32_e32 v243, 0x7000, v170
	v_add_u32_e32 v244, 0x7800, v170
	v_add_u32_e32 v245, 0x8000, v170
	ds_read2_b64 v[210:213], v242 offset0:128 offset1:132
	ds_read2_b64 v[214:217], v243 offset0:160 offset1:164
	ds_read2_b64 v[218:221], v244 offset0:192 offset1:196
	ds_read2_b64 v[222:225], v245 offset0:224 offset1:228
	ds_read2_b64 v[226:229], v242 offset0:136 offset1:140
	ds_read2_b64 v[230:233], v243 offset0:168 offset1:172
	ds_read2_b64 v[234:237], v244 offset0:200 offset1:204
	ds_read2_b64 v[238:241], v245 offset0:232 offset1:236
	v_pk_mul_f32 v[202:203], v[52:53], v[126:127] op_sel_hi:[1,0]
	v_pk_mul_f32 v[52:53], v[56:57], v[126:127] op_sel_hi:[1,0]
	v_pk_mul_f32 v[198:199], v[48:49], v[126:127] op_sel_hi:[1,0]
	v_pk_mul_f32 v[48:49], v[60:61], v[126:127] op_sel_hi:[1,0]
	v_pk_mul_f32 v[200:201], v[50:51], v[126:127] op_sel_hi:[1,0]
	v_pk_mul_f32 v[204:205], v[54:55], v[126:127] op_sel_hi:[1,0]
	v_pk_add_f32 v[64:65], v[154:155], 0 op_sel_hi:[1,0]
	v_pk_add_f32 v[80:81], v[156:157], v[64:65]
	v_pk_mul_f32 v[46:47], v[46:47], v[82:83] op_sel_hi:[1,0]
	v_pk_mul_f32 v[44:45], v[44:45], v[82:83] op_sel_hi:[1,0]
	v_pk_mul_f32 v[54:55], v[58:59], v[126:127] op_sel_hi:[1,0]
	v_cvt_pk_bf16_f32 v56, v155, v157
	v_cvt_pk_bf16_f32 v57, v151, v153
	v_cvt_pk_bf16_f32 v58, v117, v119
	v_cvt_pk_bf16_f32 v59, v123, v121
	v_cvt_pk_bf16_f32 v68, v154, v156
	s_waitcnt lgkmcnt(7)
; DEVI unsigned pk_bf16(float lo, float hi) { unsigned r; asm("v_cvt_pk_bf16_f32 %0, %1, %2" : "=v"(r) : "v"(lo), "v"(hi)); return r; }
; DEVI bf16x8 mk8(uint2 a, uint2 b) { union { uint4 u; bf16x8 v; } c; c.u = make_uint4(a.x, a.y, b.x, b.y); return c.v; }
; #define MFMA(a, b, c) __builtin_amdgcn_mfma_f32_16x16x32_bf16((a), (b), (c), 0, 0, 0)
; template <int DK, bool BIAS> ...
;     ...
;         {
;           const float alpha = __builtin_amdgcn_exp2f(mold - mnew);
;           lrun[qi] *= alpha;
; #pragma unroll
;           for (int et = 0; et < 4; ++et) O[et][qi] *= alpha;
;         }
;         lrun[qi] += ps;
; #pragma unroll
;         for (int k2 = 0; k2 < 2; ++k2) { uint2 lo, hi; lo.x = pk_bf16(S[2 * k2][qi][0], S[2 * k2][qi][1]); lo.y = pk_bf16(S[2 * k2][qi][2], S[2 * k2][qi][3]);
;           hi.x = pk_bf16(S[2 * k2 + 1][qi][0], S[2 * k2 + 1][qi][1]); hi.y = pk_bf16(S[2 * k2 + 1][qi][2], S[2 * k2 + 1][qi][3]); pf[qi][k2] = mk8(lo, hi); }
;       }
; #pragma unroll
;       for (int k2 = 0; k2 < 2; ++k2)
; #pragma unroll
;         for (int et = 0; et < 4; ++et) {
;           const uint2 v0 = *(const uint2*)(Vtm + (buf * 64 + 16 * et + fr) * 72 + 32 * k2 + 4 * fq), v1 = *(const uint2*)(Vtm + (buf * 64 + 16 * et + fr) * 72 + 32 * k2 + 16 + 4 * fq);
;           const bf16x8 va = mk8(v0, v1);
; #pragma unroll
;           for (int qi = 0; qi < 2; ++qi) O[et][qi] = MFMA(va, pf[qi][k2], O[et][qi]);
;         }
	v_mfma_f32_16x16x32_bf16 v[76:79], v[210:213], v[56:59], v[198:201]
	v_cvt_pk_bf16_f32 v69, v150, v152
	v_cvt_pk_bf16_f32 v70, v116, v118
	v_cvt_pk_bf16_f32 v71, v122, v120
	v_pk_mul_f32 v[42:43], v[42:43], v[82:83] op_sel_hi:[1,0]
	s_nop 0
	v_mfma_f32_16x16x32_bf16 v[44:47], v[210:213], v[68:71], v[44:47]
	v_pk_mul_f32 v[40:41], v[40:41], v[82:83] op_sel_hi:[1,0]
	s_waitcnt lgkmcnt(6)
	v_mfma_f32_16x16x32_bf16 v[84:87], v[214:217], v[56:59], v[202:205]
	v_pk_mul_f32 v[50:51], v[62:63], v[126:127] op_sel_hi:[1,0]
	v_mfma_f32_16x16x32_bf16 v[40:43], v[214:217], v[68:71], v[40:43]
	v_pk_mul_f32 v[38:39], v[38:39], v[82:83] op_sel_hi:[1,0]
	v_pk_mul_f32 v[36:37], v[36:37], v[82:83] op_sel_hi:[1,0]
	s_waitcnt lgkmcnt(5)
	v_mfma_f32_16x16x32_bf16 v[154:157], v[218:221], v[56:59], v[52:55]
	v_pk_mul_f32 v[34:35], v[34:35], v[82:83] op_sel_hi:[1,0]
	v_pk_mul_f32 v[32:33], v[32:33], v[82:83] op_sel_hi:[1,0]
	v_cvt_pk_bf16_f32 v60, v125, v89
	v_mfma_f32_16x16x32_bf16 v[36:39], v[218:221], v[68:71], v[36:39]
	s_waitcnt lgkmcnt(4)
	v_mfma_f32_16x16x32_bf16 v[64:67], v[222:225], v[56:59], v[48:51]
	v_cvt_pk_bf16_f32 v61, v95, v115
	v_cvt_pk_bf16_f32 v62, v93, v113
	v_cvt_pk_bf16_f32 v63, v91, v97
	s_nop 0
	v_mfma_f32_16x16x32_bf16 v[32:35], v[222:225], v[68:71], v[32:35]
	v_cvt_pk_bf16_f32 v68, v124, v88
	v_cvt_pk_bf16_f32 v69, v94, v114
	s_waitcnt lgkmcnt(3)
	v_mfma_f32_16x16x32_bf16 v[48:51], v[226:229], v[60:63], v[76:79]
	v_cvt_pk_bf16_f32 v70, v92, v112
	v_cvt_pk_bf16_f32 v71, v90, v96
	s_nop 1
	v_mfma_f32_16x16x32_bf16 v[44:47], v[226:229], v[68:71], v[44:47]
	v_pk_add_f32 v[52:53], v[150:151], v[80:81]
	v_mov_b32_e32 v83, v126
	v_pk_add_f32 v[76:77], v[152:153], v[52:53]
	s_waitcnt lgkmcnt(2)
	v_mfma_f32_16x16x32_bf16 v[52:55], v[230:233], v[60:63], v[84:87]
	v_pk_add_f32 v[76:77], v[116:117], v[76:77]
	v_pk_add_f32 v[76:77], v[118:119], v[76:77]
	v_mfma_f32_16x16x32_bf16 v[40:43], v[230:233], v[68:71], v[40:43]
	v_pk_add_f32 v[76:77], v[122:123], v[76:77]
	v_pk_add_f32 v[56:57], v[120:121], v[76:77]
	v_pk_add_f32 v[80:81], v[124:125], v[56:57]
	s_waitcnt lgkmcnt(1)
	v_mfma_f32_16x16x32_bf16 v[56:59], v[234:237], v[60:63], v[154:157]
	v_pk_add_f32 v[80:81], v[88:89], v[80:81]
	v_pk_add_f32 v[80:81], v[94:95], v[80:81]
	v_mfma_f32_16x16x32_bf16 v[36:39], v[234:237], v[68:71], v[36:39]
	v_pk_add_f32 v[80:81], v[114:115], v[80:81]
	v_mov_b32_e32 v114, v131
	v_pk_add_f32 v[72:73], v[92:93], v[80:81]
	s_waitcnt lgkmcnt(0)
	v_mfma_f32_16x16x32_bf16 v[60:63], v[238:241], v[60:63], v[64:67]
	v_pk_add_f32 v[72:73], v[112:113], v[72:73]
	v_mov_b32_e32 v112, v173
	v_mfma_f32_16x16x32_bf16 v[32:35], v[238:241], v[68:71], v[32:35]
	v_pk_add_f32 v[64:65], v[90:91], v[72:73]
	v_pk_add_f32 v[64:65], v[96:97], v[64:65]
	s_nop 0
	v_pk_fma_f32 v[106:107], v[106:107], v[82:83], v[64:65]
